# nt hint on the P10 final-output row stores (output is never re-read), on top of all row-store exchanges
# baseline (speedup 1.0000x reference)
.LBB0_1887:
	s_or_b64 exec, exec, s[0:1]
	v_lshlrev_b64 v[72:73], 2, v[176:177]
	v_lshl_add_u64 v[0:1], s[74:75], 0, v[72:73]
	s_waitcnt lgkmcnt(0)
	s_barrier
	v_and_b32_e32 v238, 7, v181
	v_lshrrev_b32_e32 v239, 7, v181
	v_bfe_u32 v240, v176, 6, 2
	v_and_b32_e32 v241, 56, v176
	v_lshl_add_u32 v242, v239, 3, v238
	v_mul_u32_u24_e32 v242, 0x410, v242
	v_lshl_add_u32 v242, v240, 8, v242
	v_lshl_add_u32 v242, v241, 2, v242
	v_add_u32_e32 v224, 0x12000, v242
	v_lshl_add_u32 v243, v239, 2, v240
	v_lshrrev_b32_e32 v244, 3, v241
	v_lshl_add_u32 v244, v238, 3, v244
	v_mul_u32_u24_e32 v243, 0x820, v243
	v_lshl_add_u32 v243, v244, 4, v243
	v_add_u32_e32 v225, 0x12000, v243
	v_lshlrev_b32_e32 v245, 1, v240
	v_sub_u32_e32 v245, v245, v238
	v_lshlrev_b32_e32 v245, 12, v245
	v_lshlrev_b32_e32 v244, 2, v244
	v_lshlrev_b32_e32 v240, 6, v240
	v_sub_u32_e32 v244, v244, v240
	v_sub_u32_e32 v244, v244, v241
	v_lshl_add_u32 v226, v244, 2, v245
	v_add_u32_e32 v226, 0x800, v226
	v_ashrrev_i32_e32 v227, 31, v226
	global_load_dwordx4 v[4:7], v[0:1], off
	s_nop 0
	global_load_dwordx4 v[0:3], v[0:1], off offset:16
	v_or_b32_e32 v79, 16, v181
	s_add_i32 s0, 0, 0x25000
	v_or_b32_e32 v97, 24, v181
	v_add_u32_e32 v96, s14, v79
	v_add_u32_e32 v74, s14, v181
	v_or_b32_e32 v77, 8, v181
	v_lshl_add_u32 v101, v97, 2, s0
	v_add_u32_e32 v130, s14, v97
	v_ashrrev_i32_e32 v97, 31, v96
	v_or_b32_e32 v133, 48, v181
	v_or_b32_e32 v135, 56, v181
	v_ashrrev_i32_e32 v75, 31, v74
	v_add_u32_e32 v78, s14, v77
	v_lshlrev_b64 v[96:97], 12, v[96:97]
	v_or_b32_e32 v109, 40, v181
	v_lshl_add_u32 v98, v181, 2, s0
	v_lshl_add_u32 v99, v77, 2, s0
	v_lshl_add_u32 v77, v79, 2, s0
	v_lshl_add_u32 v106, v133, 2, s0
	v_lshl_add_u32 v107, v135, 2, s0
	v_lshlrev_b64 v[74:75], 12, v[74:75]
	v_ashrrev_i32_e32 v79, 31, v78
	v_lshl_add_u64 v[96:97], s[76:77], 0, v[96:97]
	v_lshl_add_u32 v103, v168, 2, s0
	v_lshl_add_u32 v105, v109, 2, s0
	ds_read_b32 v98, v98
	ds_read_b32 v100, v99
	ds_read_b32 v102, v77
	ds_read_b32 v104, v101
	ds_read_b32 v132, v103
	ds_read_b32 v134, v105
	ds_read_b32 v170, v106
	ds_read_b32 v172, v107
	v_lshl_add_u64 v[74:75], s[76:77], 0, v[74:75]
	v_lshlrev_b64 v[78:79], 12, v[78:79]
	v_lshl_add_u64 v[174:175], v[96:97], 0, v[72:73]
	s_waitcnt lgkmcnt(7)
	v_pk_mul_f32 v[96:97], v[112:113], v[98:99] op_sel_hi:[1,0]
	v_pk_mul_f32 v[106:107], v[114:115], v[98:99] op_sel_hi:[1,0]
	v_lshl_add_u64 v[74:75], v[74:75], 0, v[72:73]
	v_lshl_add_u64 v[78:79], s[76:77], 0, v[78:79]
	v_pk_mul_f32 v[110:111], v[116:117], v[98:99] op_sel_hi:[1,0]
	v_pk_mul_f32 v[112:113], v[118:119], v[98:99] op_sel_hi:[1,0]
	s_waitcnt lgkmcnt(6)
	v_pk_mul_f32 v[114:115], v[120:121], v[100:101] op_sel_hi:[1,0]
	v_pk_mul_f32 v[116:117], v[122:123], v[100:101] op_sel_hi:[1,0]
	v_pk_mul_f32 v[118:119], v[124:125], v[100:101] op_sel_hi:[1,0]
	v_pk_mul_f32 v[120:121], v[126:127], v[100:101] op_sel_hi:[1,0]
	s_waitcnt lgkmcnt(5)
	v_pk_mul_f32 v[122:123], v[160:161], v[102:103] op_sel_hi:[1,0]
	v_pk_mul_f32 v[124:125], v[156:157], v[102:103] op_sel_hi:[1,0]
	v_pk_mul_f32 v[126:127], v[162:163], v[102:103] op_sel_hi:[1,0]
	v_pk_mul_f32 v[128:129], v[158:159], v[102:103] op_sel_hi:[1,0]
	v_ashrrev_i32_e32 v131, 31, v130
	v_lshl_add_u64 v[78:79], v[78:79], 0, v[72:73]
	s_waitcnt lgkmcnt(4)
	v_pk_mul_f32 v[156:157], v[164:165], v[104:105] op_sel_hi:[1,0]
	v_pk_mul_f32 v[152:153], v[152:153], v[104:105] op_sel_hi:[1,0]
	v_pk_mul_f32 v[158:159], v[166:167], v[104:105] op_sel_hi:[1,0]
	v_pk_mul_f32 v[154:155], v[154:155], v[104:105] op_sel_hi:[1,0]
	v_or_b32_e32 v77, 0x48, v181
	s_add_i32 s49, s49, s33
	s_cmpk_gt_i32 s49, 0x1ff
	s_waitcnt vmcnt(1)
	v_pk_mul_f32 v[98:99], v[6:7], v[106:107]
	v_pk_mul_f32 v[96:97], v[4:5], v[96:97]
	s_waitcnt vmcnt(0)
	v_pk_mul_f32 v[102:103], v[2:3], v[112:113]
	v_pk_mul_f32 v[100:101], v[0:1], v[110:111]
	v_pk_mul_f32 v[106:107], v[6:7], v[116:117]
	v_pk_mul_f32 v[104:105], v[4:5], v[114:115]
	v_pk_mul_f32 v[112:113], v[2:3], v[120:121]
	v_pk_mul_f32 v[110:111], v[0:1], v[118:119]
	v_pk_mul_f32 v[116:117], v[6:7], v[124:125]
	v_pk_mul_f32 v[114:115], v[4:5], v[122:123]
	v_pk_mul_f32 v[120:121], v[2:3], v[128:129]
	v_pk_mul_f32 v[118:119], v[0:1], v[126:127]
	ds_write_b128 v224, v[96:99]
	ds_write_b128 v224, v[100:103] offset:16
	v_lshl_add_u64 v[228:229], v[74:75], 0, v[226:227]
	s_waitcnt lgkmcnt(0)
	s_barrier
	ds_read_b128 v[230:233], v225
	ds_read_b128 v[234:237], v225 offset:1040
	s_waitcnt lgkmcnt(0)
	s_barrier
	global_store_dwordx4 v[228:229], v[230:233], off offset:-2048 nt
	global_store_dwordx4 v[228:229], v[234:237], off offset:2048 nt
	ds_write_b128 v224, v[104:107]
	ds_write_b128 v224, v[110:113] offset:16
	v_lshl_add_u64 v[228:229], v[78:79], 0, v[226:227]
	s_waitcnt lgkmcnt(0)
	s_barrier
	ds_read_b128 v[230:233], v225
	ds_read_b128 v[234:237], v225 offset:1040
	s_waitcnt lgkmcnt(0)
	s_barrier
	global_store_dwordx4 v[228:229], v[230:233], off offset:-2048 nt
	global_store_dwordx4 v[228:229], v[234:237], off offset:2048 nt
	ds_write_b128 v224, v[114:117]
	ds_write_b128 v224, v[118:121] offset:16
	v_lshl_add_u64 v[228:229], v[174:175], 0, v[226:227]
	s_waitcnt lgkmcnt(0)
	s_barrier
	ds_read_b128 v[230:233], v225
	ds_read_b128 v[234:237], v225 offset:1040
	s_waitcnt lgkmcnt(0)
	s_barrier
	global_store_dwordx4 v[228:229], v[230:233], off offset:-2048 nt
	global_store_dwordx4 v[228:229], v[234:237], off offset:2048 nt
	v_lshlrev_b64 v[74:75], 12, v[130:131]
	v_lshl_add_u64 v[74:75], s[76:77], 0, v[74:75]
	v_pk_mul_f32 v[124:125], v[6:7], v[152:153]
	v_pk_mul_f32 v[122:123], v[4:5], v[156:157]
	v_lshl_add_u64 v[74:75], v[74:75], 0, v[72:73]
	v_pk_mul_f32 v[128:129], v[2:3], v[154:155]
	v_pk_mul_f32 v[126:127], v[0:1], v[158:159]
	ds_write_b128 v224, v[122:125]
	ds_write_b128 v224, v[126:129] offset:16
	v_lshl_add_u64 v[228:229], v[74:75], 0, v[226:227]
	s_waitcnt lgkmcnt(0)
	s_barrier
	ds_read_b128 v[230:233], v225
	ds_read_b128 v[234:237], v225 offset:1040
	s_waitcnt lgkmcnt(0)
	s_barrier
	global_store_dwordx4 v[228:229], v[230:233], off offset:-2048 nt
	global_store_dwordx4 v[228:229], v[234:237], off offset:2048 nt
	v_add_u32_e32 v74, s14, v168
	v_ashrrev_i32_e32 v75, 31, v74
	v_lshlrev_b64 v[74:75], 12, v[74:75]
	s_waitcnt lgkmcnt(3)
	v_pk_mul_f32 v[78:79], v[80:81], v[132:133] op_sel_hi:[1,0]
	v_pk_mul_f32 v[80:81], v[82:83], v[132:133] op_sel_hi:[1,0]
	v_lshl_add_u64 v[74:75], s[76:77], 0, v[74:75]
	v_pk_mul_f32 v[80:81], v[6:7], v[80:81]
	v_pk_mul_f32 v[78:79], v[4:5], v[78:79]
	v_pk_mul_f32 v[82:83], v[84:85], v[132:133] op_sel_hi:[1,0]
	v_pk_mul_f32 v[84:85], v[86:87], v[132:133] op_sel_hi:[1,0]
	v_lshl_add_u64 v[74:75], v[74:75], 0, v[72:73]
	v_pk_mul_f32 v[84:85], v[2:3], v[84:85]
	v_pk_mul_f32 v[82:83], v[0:1], v[82:83]
	ds_write_b128 v224, v[78:81]
	ds_write_b128 v224, v[82:85] offset:16
	v_lshl_add_u64 v[228:229], v[74:75], 0, v[226:227]
	s_waitcnt lgkmcnt(0)
	s_barrier
	ds_read_b128 v[230:233], v225
	ds_read_b128 v[234:237], v225 offset:1040
	s_waitcnt lgkmcnt(0)
	s_barrier
	global_store_dwordx4 v[228:229], v[230:233], off offset:-2048 nt
	global_store_dwordx4 v[228:229], v[234:237], off offset:2048 nt
	v_add_u32_e32 v74, s14, v109
	v_ashrrev_i32_e32 v75, 31, v74
	v_lshlrev_b64 v[74:75], 12, v[74:75]
	s_waitcnt lgkmcnt(2)
	v_pk_mul_f32 v[78:79], v[88:89], v[134:135] op_sel_hi:[1,0]
	v_pk_mul_f32 v[80:81], v[90:91], v[134:135] op_sel_hi:[1,0]
	v_lshl_add_u64 v[74:75], s[76:77], 0, v[74:75]
	v_pk_mul_f32 v[80:81], v[6:7], v[80:81]
	v_pk_mul_f32 v[78:79], v[4:5], v[78:79]
	v_pk_mul_f32 v[82:83], v[92:93], v[134:135] op_sel_hi:[1,0]
	v_pk_mul_f32 v[84:85], v[94:95], v[134:135] op_sel_hi:[1,0]
	v_lshl_add_u64 v[74:75], v[74:75], 0, v[72:73]
	v_pk_mul_f32 v[84:85], v[2:3], v[84:85]
	v_pk_mul_f32 v[82:83], v[0:1], v[82:83]
	ds_write_b128 v224, v[78:81]
	ds_write_b128 v224, v[82:85] offset:16
	v_lshl_add_u64 v[228:229], v[74:75], 0, v[226:227]
	s_waitcnt lgkmcnt(0)
	s_barrier
	ds_read_b128 v[230:233], v225
	ds_read_b128 v[234:237], v225 offset:1040
	s_waitcnt lgkmcnt(0)
	s_barrier
	global_store_dwordx4 v[228:229], v[230:233], off offset:-2048 nt
	global_store_dwordx4 v[228:229], v[234:237], off offset:2048 nt
	v_add_u32_e32 v74, s14, v133
	v_ashrrev_i32_e32 v75, 31, v74
	v_lshlrev_b64 v[74:75], 12, v[74:75]
	s_waitcnt lgkmcnt(1)
	v_pk_mul_f32 v[78:79], v[144:145], v[170:171] op_sel_hi:[1,0]
	v_pk_mul_f32 v[80:81], v[140:141], v[170:171] op_sel_hi:[1,0]
	v_lshl_add_u64 v[74:75], s[76:77], 0, v[74:75]
	v_pk_mul_f32 v[80:81], v[6:7], v[80:81]
	v_pk_mul_f32 v[78:79], v[4:5], v[78:79]
	v_pk_mul_f32 v[82:83], v[146:147], v[170:171] op_sel_hi:[1,0]
	v_pk_mul_f32 v[84:85], v[142:143], v[170:171] op_sel_hi:[1,0]
	v_lshl_add_u64 v[74:75], v[74:75], 0, v[72:73]
	v_pk_mul_f32 v[84:85], v[2:3], v[84:85]
	v_pk_mul_f32 v[82:83], v[0:1], v[82:83]
	ds_write_b128 v224, v[78:81]
	ds_write_b128 v224, v[82:85] offset:16
	v_lshl_add_u64 v[228:229], v[74:75], 0, v[226:227]
	s_waitcnt lgkmcnt(0)
	s_barrier
	ds_read_b128 v[230:233], v225
	ds_read_b128 v[234:237], v225 offset:1040
	s_waitcnt lgkmcnt(0)
	s_barrier
	global_store_dwordx4 v[228:229], v[230:233], off offset:-2048 nt
	global_store_dwordx4 v[228:229], v[234:237], off offset:2048 nt
	v_add_u32_e32 v74, s14, v135
	v_ashrrev_i32_e32 v75, 31, v74
	v_lshlrev_b64 v[74:75], 12, v[74:75]
	s_waitcnt lgkmcnt(0)
	v_pk_mul_f32 v[78:79], v[148:149], v[172:173] op_sel_hi:[1,0]
	v_pk_mul_f32 v[80:81], v[136:137], v[172:173] op_sel_hi:[1,0]
	v_pk_mul_f32 v[82:83], v[150:151], v[172:173] op_sel_hi:[1,0]
	v_lshl_add_u64 v[74:75], s[76:77], 0, v[74:75]
	v_pk_mul_f32 v[80:81], v[6:7], v[80:81]
	v_pk_mul_f32 v[78:79], v[4:5], v[78:79]
	v_pk_mul_f32 v[84:85], v[138:139], v[172:173] op_sel_hi:[1,0]
	v_pk_mul_f32 v[82:83], v[0:1], v[82:83]
	v_lshl_add_u64 v[74:75], v[74:75], 0, v[72:73]
	v_pk_mul_f32 v[84:85], v[2:3], v[84:85]
	ds_write_b128 v224, v[78:81]
	ds_write_b128 v224, v[82:85] offset:16
	v_lshl_add_u64 v[228:229], v[74:75], 0, v[226:227]
	s_waitcnt lgkmcnt(0)
	s_barrier
	ds_read_b128 v[230:233], v225
	ds_read_b128 v[234:237], v225 offset:1040
	s_waitcnt lgkmcnt(0)
	s_barrier
	global_store_dwordx4 v[228:229], v[230:233], off offset:-2048 nt
	global_store_dwordx4 v[228:229], v[234:237], off offset:2048 nt
	v_or_b32_e32 v87, 0x68, v181
	v_or_b32_e32 v81, 0x50, v181
	v_or_b32_e32 v83, 0x58, v181
	v_or_b32_e32 v89, 0x70, v181
	v_or_b32_e32 v91, 0x78, v181
	v_lshl_add_u32 v75, v108, 2, s0
	v_add_u32_e32 v74, s14, v108
	v_lshl_add_u32 v82, v81, 2, s0
	v_lshl_add_u32 v84, v83, 2, s0
	v_lshl_add_u32 v88, v87, 2, s0
	v_lshl_add_u32 v90, v89, 2, s0
	v_lshl_add_u32 v92, v91, 2, s0
	v_lshl_add_u32 v79, v77, 2, s0
	v_lshl_add_u32 v85, v76, 2, s0
	ds_read_b32 v78, v75
	ds_read_b32 v80, v79
	ds_read_b32 v82, v82
	ds_read_b32 v84, v84
	ds_read_b32 v86, v85
	ds_read_b32 v88, v88
	ds_read_b32 v90, v90
	ds_read_b32 v92, v92
	v_ashrrev_i32_e32 v75, 31, v74
	v_lshlrev_b64 v[74:75], 12, v[74:75]
	s_waitcnt lgkmcnt(7)
	v_pk_mul_f32 v[32:33], v[32:33], v[78:79] op_sel_hi:[1,0]
	v_pk_mul_f32 v[34:35], v[34:35], v[78:79] op_sel_hi:[1,0]
	v_lshl_add_u64 v[74:75], s[76:77], 0, v[74:75]
	v_pk_mul_f32 v[34:35], v[6:7], v[34:35]
	v_pk_mul_f32 v[32:33], v[4:5], v[32:33]
	v_pk_mul_f32 v[36:37], v[36:37], v[78:79] op_sel_hi:[1,0]
	v_pk_mul_f32 v[38:39], v[38:39], v[78:79] op_sel_hi:[1,0]
	v_lshl_add_u64 v[74:75], v[74:75], 0, v[72:73]
	v_pk_mul_f32 v[38:39], v[2:3], v[38:39]
	v_pk_mul_f32 v[36:37], v[0:1], v[36:37]
	ds_write_b128 v224, v[32:35]
	ds_write_b128 v224, v[36:39] offset:16
	v_lshl_add_u64 v[228:229], v[74:75], 0, v[226:227]
	s_waitcnt lgkmcnt(0)
	s_barrier
	ds_read_b128 v[230:233], v225
	ds_read_b128 v[234:237], v225 offset:1040
	s_waitcnt lgkmcnt(0)
	s_barrier
	global_store_dwordx4 v[228:229], v[230:233], off offset:-2048 nt
	global_store_dwordx4 v[228:229], v[234:237], off offset:2048 nt
	v_add_u32_e32 v74, s14, v77
	v_ashrrev_i32_e32 v75, 31, v74
	s_waitcnt lgkmcnt(6)
	v_pk_mul_f32 v[32:33], v[40:41], v[80:81] op_sel_hi:[1,0]
	v_lshlrev_b64 v[40:41], 12, v[74:75]
	v_pk_mul_f32 v[34:35], v[42:43], v[80:81] op_sel_hi:[1,0]
	v_lshl_add_u64 v[40:41], s[76:77], 0, v[40:41]
	v_pk_mul_f32 v[34:35], v[6:7], v[34:35]
	v_pk_mul_f32 v[32:33], v[4:5], v[32:33]
	v_pk_mul_f32 v[36:37], v[44:45], v[80:81] op_sel_hi:[1,0]
	v_pk_mul_f32 v[38:39], v[46:47], v[80:81] op_sel_hi:[1,0]
	v_lshl_add_u64 v[40:41], v[40:41], 0, v[72:73]
	v_pk_mul_f32 v[38:39], v[2:3], v[38:39]
	v_pk_mul_f32 v[36:37], v[0:1], v[36:37]
	ds_write_b128 v224, v[32:35]
	ds_write_b128 v224, v[36:39] offset:16
	v_lshl_add_u64 v[228:229], v[40:41], 0, v[226:227]
	s_waitcnt lgkmcnt(0)
	s_barrier
	ds_read_b128 v[230:233], v225
	ds_read_b128 v[234:237], v225 offset:1040
	s_waitcnt lgkmcnt(0)
	s_barrier
	global_store_dwordx4 v[228:229], v[230:233], off offset:-2048 nt
	global_store_dwordx4 v[228:229], v[234:237], off offset:2048 nt
	v_add_u32_e32 v40, s14, v81
	v_ashrrev_i32_e32 v41, 31, v40
	v_lshlrev_b64 v[40:41], 12, v[40:41]
	s_waitcnt lgkmcnt(5)
	v_pk_mul_f32 v[32:33], v[48:49], v[82:83] op_sel_hi:[1,0]
	v_pk_mul_f32 v[34:35], v[50:51], v[82:83] op_sel_hi:[1,0]
	v_lshl_add_u64 v[40:41], s[76:77], 0, v[40:41]
	v_pk_mul_f32 v[34:35], v[6:7], v[34:35]
	v_pk_mul_f32 v[32:33], v[4:5], v[32:33]
	v_pk_mul_f32 v[36:37], v[52:53], v[82:83] op_sel_hi:[1,0]
	v_pk_mul_f32 v[38:39], v[54:55], v[82:83] op_sel_hi:[1,0]
	v_lshl_add_u64 v[40:41], v[40:41], 0, v[72:73]
	v_pk_mul_f32 v[38:39], v[2:3], v[38:39]
	v_pk_mul_f32 v[36:37], v[0:1], v[36:37]
	ds_write_b128 v224, v[32:35]
	ds_write_b128 v224, v[36:39] offset:16
	v_lshl_add_u64 v[228:229], v[40:41], 0, v[226:227]
	s_waitcnt lgkmcnt(0)
	s_barrier
	ds_read_b128 v[230:233], v225
	ds_read_b128 v[234:237], v225 offset:1040
	s_waitcnt lgkmcnt(0)
	s_barrier
	global_store_dwordx4 v[228:229], v[230:233], off offset:-2048 nt
	global_store_dwordx4 v[228:229], v[234:237], off offset:2048 nt
	v_add_u32_e32 v40, s14, v83
	v_ashrrev_i32_e32 v41, 31, v40
	v_lshlrev_b64 v[40:41], 12, v[40:41]
	s_waitcnt lgkmcnt(4)
	v_pk_mul_f32 v[32:33], v[56:57], v[84:85] op_sel_hi:[1,0]
	v_pk_mul_f32 v[34:35], v[58:59], v[84:85] op_sel_hi:[1,0]
	v_lshl_add_u64 v[40:41], s[76:77], 0, v[40:41]
	v_pk_mul_f32 v[34:35], v[6:7], v[34:35]
	v_pk_mul_f32 v[32:33], v[4:5], v[32:33]
	v_pk_mul_f32 v[36:37], v[60:61], v[84:85] op_sel_hi:[1,0]
	v_pk_mul_f32 v[38:39], v[62:63], v[84:85] op_sel_hi:[1,0]
	v_lshl_add_u64 v[40:41], v[40:41], 0, v[72:73]
	v_pk_mul_f32 v[38:39], v[2:3], v[38:39]
	v_pk_mul_f32 v[36:37], v[0:1], v[36:37]
	ds_write_b128 v224, v[32:35]
	ds_write_b128 v224, v[36:39] offset:16
	v_lshl_add_u64 v[228:229], v[40:41], 0, v[226:227]
	s_waitcnt lgkmcnt(0)
	s_barrier
	ds_read_b128 v[230:233], v225
	ds_read_b128 v[234:237], v225 offset:1040
	s_waitcnt lgkmcnt(0)
	s_barrier
	global_store_dwordx4 v[228:229], v[230:233], off offset:-2048 nt
	global_store_dwordx4 v[228:229], v[234:237], off offset:2048 nt
	s_waitcnt lgkmcnt(3)
	v_pk_mul_f32 v[8:9], v[8:9], v[86:87] op_sel_hi:[1,0]
	v_add_u32_e32 v32, s14, v76
	v_ashrrev_i32_e32 v33, 31, v32
	v_lshlrev_b64 v[32:33], 12, v[32:33]
	v_pk_mul_f32 v[10:11], v[10:11], v[86:87] op_sel_hi:[1,0]
	v_lshl_add_u64 v[32:33], s[76:77], 0, v[32:33]
	v_pk_mul_f32 v[10:11], v[6:7], v[10:11]
	v_pk_mul_f32 v[8:9], v[4:5], v[8:9]
	v_pk_mul_f32 v[12:13], v[12:13], v[86:87] op_sel_hi:[1,0]
	v_pk_mul_f32 v[14:15], v[14:15], v[86:87] op_sel_hi:[1,0]
	v_lshl_add_u64 v[32:33], v[32:33], 0, v[72:73]
	v_pk_mul_f32 v[14:15], v[2:3], v[14:15]
	v_pk_mul_f32 v[12:13], v[0:1], v[12:13]
	ds_write_b128 v224, v[8:11]
	ds_write_b128 v224, v[12:15] offset:16
	v_lshl_add_u64 v[228:229], v[32:33], 0, v[226:227]
	s_waitcnt lgkmcnt(0)
	s_barrier
	ds_read_b128 v[230:233], v225
	ds_read_b128 v[234:237], v225 offset:1040
	s_waitcnt lgkmcnt(0)
	s_barrier
	global_store_dwordx4 v[228:229], v[230:233], off offset:-2048 nt
	global_store_dwordx4 v[228:229], v[234:237], off offset:2048 nt
	v_add_u32_e32 v32, s14, v87
	v_ashrrev_i32_e32 v33, 31, v32
	s_waitcnt lgkmcnt(2)
	v_pk_mul_f32 v[8:9], v[16:17], v[88:89] op_sel_hi:[1,0]
	v_lshlrev_b64 v[16:17], 12, v[32:33]
	v_pk_mul_f32 v[10:11], v[18:19], v[88:89] op_sel_hi:[1,0]
	v_lshl_add_u64 v[16:17], s[76:77], 0, v[16:17]
	v_pk_mul_f32 v[10:11], v[6:7], v[10:11]
	v_pk_mul_f32 v[8:9], v[4:5], v[8:9]
	v_pk_mul_f32 v[12:13], v[20:21], v[88:89] op_sel_hi:[1,0]
	v_pk_mul_f32 v[14:15], v[22:23], v[88:89] op_sel_hi:[1,0]
	v_lshl_add_u64 v[16:17], v[16:17], 0, v[72:73]
	v_pk_mul_f32 v[14:15], v[2:3], v[14:15]
	v_pk_mul_f32 v[12:13], v[0:1], v[12:13]
	ds_write_b128 v224, v[8:11]
	ds_write_b128 v224, v[12:15] offset:16
	v_lshl_add_u64 v[228:229], v[16:17], 0, v[226:227]
	s_waitcnt lgkmcnt(0)
	s_barrier
	ds_read_b128 v[230:233], v225
	ds_read_b128 v[234:237], v225 offset:1040
	s_waitcnt lgkmcnt(0)
	s_barrier
	global_store_dwordx4 v[228:229], v[230:233], off offset:-2048 nt
	global_store_dwordx4 v[228:229], v[234:237], off offset:2048 nt
	v_add_u32_e32 v16, s14, v89
	v_ashrrev_i32_e32 v17, 31, v16
	v_lshlrev_b64 v[16:17], 12, v[16:17]
	s_waitcnt lgkmcnt(1)
	v_pk_mul_f32 v[8:9], v[24:25], v[90:91] op_sel_hi:[1,0]
	v_pk_mul_f32 v[10:11], v[26:27], v[90:91] op_sel_hi:[1,0]
	v_lshl_add_u64 v[16:17], s[76:77], 0, v[16:17]
	v_pk_mul_f32 v[10:11], v[6:7], v[10:11]
	v_pk_mul_f32 v[8:9], v[4:5], v[8:9]
	v_pk_mul_f32 v[12:13], v[28:29], v[90:91] op_sel_hi:[1,0]
	v_pk_mul_f32 v[14:15], v[30:31], v[90:91] op_sel_hi:[1,0]
	v_lshl_add_u64 v[16:17], v[16:17], 0, v[72:73]
	v_pk_mul_f32 v[14:15], v[2:3], v[14:15]
	v_pk_mul_f32 v[12:13], v[0:1], v[12:13]
	ds_write_b128 v224, v[8:11]
	ds_write_b128 v224, v[12:15] offset:16
	v_lshl_add_u64 v[228:229], v[16:17], 0, v[226:227]
	s_waitcnt lgkmcnt(0)
	s_barrier
	ds_read_b128 v[230:233], v225
	ds_read_b128 v[234:237], v225 offset:1040
	s_waitcnt lgkmcnt(0)
	s_barrier
	global_store_dwordx4 v[228:229], v[230:233], off offset:-2048 nt
	global_store_dwordx4 v[228:229], v[234:237], off offset:2048 nt
	s_nop 0
	v_add_u32_e32 v8, s14, v91
	v_ashrrev_i32_e32 v9, 31, v8
	s_waitcnt lgkmcnt(0)
	v_pk_mul_f32 v[10:11], v[68:69], v[92:93] op_sel_hi:[1,0]
	v_pk_mul_f32 v[12:13], v[64:65], v[92:93] op_sel_hi:[1,0]
	v_lshlrev_b64 v[8:9], 12, v[8:9]
	v_pk_mul_f32 v[6:7], v[6:7], v[12:13]
	v_pk_mul_f32 v[4:5], v[4:5], v[10:11]
	v_pk_mul_f32 v[10:11], v[70:71], v[92:93] op_sel_hi:[1,0]
	v_pk_mul_f32 v[12:13], v[66:67], v[92:93] op_sel_hi:[1,0]
	v_lshl_add_u64 v[8:9], s[76:77], 0, v[8:9]
	v_pk_mul_f32 v[2:3], v[2:3], v[12:13]
	v_pk_mul_f32 v[0:1], v[0:1], v[10:11]
	v_lshl_add_u64 v[8:9], v[8:9], 0, v[72:73]
	ds_write_b128 v224, v[4:7]
	ds_write_b128 v224, v[0:3] offset:16
	v_lshl_add_u64 v[228:229], v[8:9], 0, v[226:227]
	s_waitcnt lgkmcnt(0)
	s_barrier
	ds_read_b128 v[230:233], v225
	ds_read_b128 v[234:237], v225 offset:1040
	s_waitcnt lgkmcnt(0)
	s_barrier
	global_store_dwordx4 v[228:229], v[230:233], off offset:-2048 nt
	global_store_dwordx4 v[228:229], v[234:237], off offset:2048 nt
	s_cbranch_scc1 .LBB0_2014
